# q/k RoPE epilogue: all 32 cos/sin table row loads issued up front into unused registers (single wait) instead of load + vmcnt(0) per token row
# speedup vs baseline: 1.0047x; 1.0047x over previous
; DI int crow(int reg, int g) { return (reg & 3) + 8 * (reg >> 2) + 4 * g; }
; template <bool TR>
; DI void gemm_in_tile(const P& p, int l, int id, char* smem) {
;     ...
;   } else if (nt < 12) {
;     const bool isq = nt < 10;
;     const int h = (nt & 1) * 2 + wc;
;     u16* dst = isq ? p.Qb : p.Kb;
;     const float qs = isq ? (0.125f * 1.4426950408889634f) : 1.0f;
;     float kl0 = 0.f, kl1 = 0.f;
; #pragma unroll
;     for (int rb = 0; rb < 2; ++rb) {
; #pragma unroll
;       for (int reg = 0; reg < 16; ++reg) {
;         if ((reg & 7) == 0) asm volatile("" ::: "memory");
;         const int rl = 64 * wr + 32 * rb + crow(reg, g);
;         const int tok = m0 + rl;
;         const float rs = rs_s[rl] * qs;
;         const int pos = tok & 8191, b = tok >> 13;
;         const float2 cs = p.rope[pos * 32 + li];
.LBB0_332:
	s_andn2_b64 vcc, exec, s[8:9]
	s_cbranch_vccnz .LBB0_337
	v_add_u32_e32 v136, s76, v144
	v_and_b32_e32 v140, 0x1fc4, v136
	v_lshlrev_b32_e32 v137, 3, v177
	v_mov_b32_e32 v249, v144
	v_add_u32_e32 v249, s76, v249
	v_and_b32_e32 v249, 0x1fff, v249
	v_lshl_or_b32 v249, v249, 8, v137
	global_load_dwordx2 v[146:147], v249, s[50:51]
	v_or_b32_e32 v249, 1, v144
	v_add_u32_e32 v249, s76, v249
	v_and_b32_e32 v249, 0x1fff, v249
	v_lshl_or_b32 v249, v249, 8, v137
	global_load_dwordx2 v[148:149], v249, s[50:51]
	v_or_b32_e32 v249, 2, v144
	v_add_u32_e32 v249, s76, v249
	v_and_b32_e32 v249, 0x1fff, v249
	v_lshl_or_b32 v249, v249, 8, v137
	global_load_dwordx2 v[150:151], v249, s[50:51]
	v_or_b32_e32 v249, 3, v144
	v_add_u32_e32 v249, s76, v249
	v_and_b32_e32 v249, 0x1fff, v249
	v_lshl_or_b32 v249, v249, 8, v137
	global_load_dwordx2 v[152:153], v249, s[50:51]
	v_or_b32_e32 v249, 8, v144
	v_add_u32_e32 v249, s76, v249
	v_and_b32_e32 v249, 0x1fff, v249
	v_lshl_or_b32 v249, v249, 8, v137
	global_load_dwordx2 v[154:155], v249, s[50:51]
	v_or_b32_e32 v249, 9, v144
	v_add_u32_e32 v249, s76, v249
	v_and_b32_e32 v249, 0x1fff, v249
	v_lshl_or_b32 v249, v249, 8, v137
	global_load_dwordx2 v[156:157], v249, s[50:51]
	v_or_b32_e32 v249, 10, v144
	v_add_u32_e32 v249, s76, v249
	v_and_b32_e32 v249, 0x1fff, v249
	v_lshl_or_b32 v249, v249, 8, v137
	global_load_dwordx2 v[158:159], v249, s[50:51]
	v_or_b32_e32 v249, 11, v144
	v_add_u32_e32 v249, s76, v249
	v_and_b32_e32 v249, 0x1fff, v249
	v_lshl_or_b32 v249, v249, 8, v137
	global_load_dwordx2 v[160:161], v249, s[50:51]
	v_or_b32_e32 v249, 16, v144
	v_add_u32_e32 v249, s76, v249
	v_and_b32_e32 v249, 0x1fff, v249
	v_lshl_or_b32 v249, v249, 8, v137
	global_load_dwordx2 v[162:163], v249, s[50:51]
	v_or_b32_e32 v249, 17, v144
	v_add_u32_e32 v249, s76, v249
	v_and_b32_e32 v249, 0x1fff, v249
	v_lshl_or_b32 v249, v249, 8, v137
	global_load_dwordx2 v[164:165], v249, s[50:51]
	v_or_b32_e32 v249, 18, v144
	v_add_u32_e32 v249, s76, v249
	v_and_b32_e32 v249, 0x1fff, v249
	v_lshl_or_b32 v249, v249, 8, v137
	global_load_dwordx2 v[166:167], v249, s[50:51]
	v_or_b32_e32 v249, 19, v144
	v_add_u32_e32 v249, s76, v249
	v_and_b32_e32 v249, 0x1fff, v249
	v_lshl_or_b32 v249, v249, 8, v137
	global_load_dwordx2 v[168:169], v249, s[50:51]
	v_or_b32_e32 v249, 24, v144
	v_add_u32_e32 v249, s76, v249
	v_and_b32_e32 v249, 0x1fff, v249
	v_lshl_or_b32 v249, v249, 8, v137
	global_load_dwordx2 v[170:171], v249, s[50:51]
	v_or_b32_e32 v249, 25, v144
	v_add_u32_e32 v249, s76, v249
	v_and_b32_e32 v249, 0x1fff, v249
	v_lshl_or_b32 v249, v249, 8, v137
	global_load_dwordx2 v[172:173], v249, s[50:51]
	v_or_b32_e32 v249, 26, v144
	v_add_u32_e32 v249, s76, v249
	v_and_b32_e32 v249, 0x1fff, v249
	v_lshl_or_b32 v249, v249, 8, v137
	global_load_dwordx2 v[174:175], v249, s[50:51]
	v_or_b32_e32 v249, 27, v144
	v_add_u32_e32 v249, s76, v249
	v_and_b32_e32 v249, 0x1fff, v249
	v_lshl_or_b32 v249, v249, 8, v137
	global_load_dwordx2 v[220:221], v249, s[50:51]
	v_or_b32_e32 v249, 32, v144
	v_add_u32_e32 v249, s76, v249
	v_and_b32_e32 v249, 0x1fff, v249
	v_lshl_or_b32 v249, v249, 8, v137
	global_load_dwordx2 v[222:223], v249, s[50:51]
	v_or_b32_e32 v249, 33, v144
	v_add_u32_e32 v249, s76, v249
	v_and_b32_e32 v249, 0x1fff, v249
	v_lshl_or_b32 v249, v249, 8, v137
	global_load_dwordx2 v[224:225], v249, s[50:51]
	v_or_b32_e32 v249, 34, v144
	v_add_u32_e32 v249, s76, v249
	v_and_b32_e32 v249, 0x1fff, v249
	v_lshl_or_b32 v249, v249, 8, v137
	global_load_dwordx2 v[226:227], v249, s[50:51]
	v_or_b32_e32 v249, 35, v144
	v_add_u32_e32 v249, s76, v249
	v_and_b32_e32 v249, 0x1fff, v249
	v_lshl_or_b32 v249, v249, 8, v137
	global_load_dwordx2 v[228:229], v249, s[50:51]
	v_or_b32_e32 v249, 40, v144
	v_add_u32_e32 v249, s76, v249
	v_and_b32_e32 v249, 0x1fff, v249
	v_lshl_or_b32 v249, v249, 8, v137
	global_load_dwordx2 v[230:231], v249, s[50:51]
	v_or_b32_e32 v249, 41, v144
	v_add_u32_e32 v249, s76, v249
	v_and_b32_e32 v249, 0x1fff, v249
	v_lshl_or_b32 v249, v249, 8, v137
	global_load_dwordx2 v[232:233], v249, s[50:51]
	v_or_b32_e32 v249, 42, v144
	v_add_u32_e32 v249, s76, v249
	v_and_b32_e32 v249, 0x1fff, v249
	v_lshl_or_b32 v249, v249, 8, v137
	global_load_dwordx2 v[234:235], v249, s[50:51]
	v_or_b32_e32 v249, 43, v144
	v_add_u32_e32 v249, s76, v249
	v_and_b32_e32 v249, 0x1fff, v249
	v_lshl_or_b32 v249, v249, 8, v137
	global_load_dwordx2 v[236:237], v249, s[50:51]
	v_or_b32_e32 v249, 48, v144
	v_add_u32_e32 v249, s76, v249
	v_and_b32_e32 v249, 0x1fff, v249
	v_lshl_or_b32 v249, v249, 8, v137
	global_load_dwordx2 v[238:239], v249, s[50:51]
	v_or_b32_e32 v249, 49, v144
	v_add_u32_e32 v249, s76, v249
	v_and_b32_e32 v249, 0x1fff, v249
	v_lshl_or_b32 v249, v249, 8, v137
	global_load_dwordx2 v[240:241], v249, s[50:51]
	v_or_b32_e32 v249, 50, v144
	v_add_u32_e32 v249, s76, v249
	v_and_b32_e32 v249, 0x1fff, v249
	v_lshl_or_b32 v249, v249, 8, v137
	global_load_dwordx2 v[242:243], v249, s[50:51]
	v_or_b32_e32 v249, 51, v144
	v_add_u32_e32 v249, s76, v249
	v_and_b32_e32 v249, 0x1fff, v249
	v_lshl_or_b32 v249, v249, 8, v137
	global_load_dwordx2 v[244:245], v249, s[50:51]
	v_or_b32_e32 v249, 56, v144
	v_add_u32_e32 v249, s76, v249
	v_and_b32_e32 v249, 0x1fff, v249
	v_lshl_or_b32 v249, v249, 8, v137
	global_load_dwordx2 v[246:247], v249, s[50:51]
	v_or_b32_e32 v249, 57, v144
	v_add_u32_e32 v249, s76, v249
	v_and_b32_e32 v249, 0x1fff, v249
	v_lshl_or_b32 v249, v249, 8, v137
	global_load_dwordx2 v[190:191], v249, s[50:51]
	v_or_b32_e32 v249, 58, v144
	v_add_u32_e32 v249, s76, v249
	v_and_b32_e32 v249, 0x1fff, v249
	v_lshl_or_b32 v249, v249, 8, v137
	global_load_dwordx2 v[192:193], v249, s[50:51]
	v_or_b32_e32 v249, 59, v144
	v_add_u32_e32 v249, s76, v249
	v_and_b32_e32 v249, 0x1fff, v249
	v_lshl_or_b32 v249, v249, 8, v137
	global_load_dwordx2 v[194:195], v249, s[50:51]
	v_lshl_or_b32 v138, v140, 8, v137
	s_cmp_lt_u32 s74, 10
	s_cselect_b64 vcc, -1, 0
	s_lshl_b32 s8, s77, 1
	v_and_or_b32 v134, s8, 2, v145
	s_and_b64 s[8:9], vcc, exec
	s_cselect_b32 s9, s41, s43
	s_cselect_b32 s8, s40, s42
	v_lshlrev_b32_e32 v188, 1, v177
	v_lshl_add_u64 v[132:133], s[8:9], 0, v[188:189]
	s_add_i32 s8, 0, 0x24000
	v_lshl_add_u32 v128, v144, 2, s8
	ds_read_b128 v[128:131], v128
	v_cndmask_b32_e32 v135, 1.0, v216, vcc
	v_lshrrev_b32_e32 v141, 11, v136
	s_mov_b32 s9, 0x3fffc
	v_and_or_b32 v141, v141, s9, v134
	s_waitcnt lgkmcnt(0)
; DI u16 f2bf(float a) { return (u16)(pack2(a, 0.f) & 0xffffu); }
; DI int crow(int reg, int g) { return (reg & 3) + 8 * (reg >> 2) + 4 * g; }
; template <bool TR>
; DI void gemm_in_tile(const P& p, int l, int id, char* smem) {
;     ...
; #pragma unroll
;     for (int rb = 0; rb < 2; ++rb) {
; #pragma unroll
;       for (int reg = 0; reg < 16; ++reg) {
;         if ((reg & 7) == 0) asm volatile("" ::: "memory");
;         const int rl = 64 * wr + 32 * rb + crow(reg, g);
;         const int tok = m0 + rl;
;         const float rs = rs_s[rl] * qs;
;         const int pos = tok & 8191, b = tok >> 13;
;         const float2 cs = p.rope[pos * 32 + li];
; #pragma unroll
;         for (int c = 0; c < 2; ++c) {
;           const float x1 = acc[rb][2 * c][reg] * rs, x2 = acc[rb][2 * c + 1][reg] * rs;
;           const float o1 = x1 * cs.x - x2 * cs.y, o2 = x2 * cs.x + x1 * cs.y;
;           const size_t base = ((size_t)(((b * 4 + h) * 2 + c) * SEQ + pos)) * 64;
;           dst[base + li] = f2bf(o1);
;           dst[base + 32 + li] = f2bf(o2);
;           if (c == 0) kl0 = fmaxf(kl0, o1 * o1 + o2 * o2); else kl1 = fmaxf(kl1, o1 * o1 + o2 * o2);
;         }
	v_mul_f32_e32 v128, v135, v128
	v_lshl_or_b32 v140, v141, 14, v140
	v_mul_f32_e32 v141, v112, v128
	v_mul_f32_e32 v112, v96, v128
	v_mul_f32_e32 v64, v64, v128
	v_mul_f32_e32 v129, v135, v129
	v_mul_f32_e32 v65, v65, v129
	v_mul_f32_e32 v130, v135, v130
	v_mul_f32_e32 v66, v66, v130
	v_mul_f32_e32 v131, v135, v131
	v_mul_f32_e32 v67, v67, v131
	s_and_b64 vcc, vcc, exec
	s_waitcnt vmcnt(0)
	v_mul_f32_e32 v96, v147, v112
	v_mul_f32_e32 v112, v146, v112
	v_fma_f32 v96, v146, v141, -v96
	v_fmac_f32_e32 v112, v147, v141
	v_ashrrev_i32_e32 v141, 31, v140
	v_lshlrev_b64 v[142:143], 7, v[140:141]
	v_lshl_add_u64 v[142:143], v[132:133], 0, v[142:143]
	v_cvt_pk_bf16_f32 v141, v112, s0
	global_store_short v[142:143], v141, off offset:64
	v_mul_f32_e32 v141, v80, v128
	v_mul_f32_e32 v80, v147, v64
	v_fma_f32 v80, v146, v141, -v80
	v_mul_f32_e32 v128, v146, v64
	v_or_b32_e32 v138, 0x2000, v140
	v_fmac_f32_e32 v128, v147, v141
	v_ashrrev_i32_e32 v139, 31, v138
	v_lshlrev_b64 v[138:139], 7, v[138:139]
	v_cvt_pk_bf16_f32 v64, v80, s0
	v_lshl_add_u64 v[138:139], v[132:133], 0, v[138:139]
	global_store_short v[138:139], v64, off
	v_cvt_pk_bf16_f32 v64, v128, s0
	global_store_short v[138:139], v64, off offset:64
	v_add_u32_e32 v64, 1, v136
	v_cvt_pk_bf16_f32 v145, v96, s0
	v_and_b32_e32 v140, 0x1ffd, v64
	global_store_short v[142:143], v145, off
	v_lshl_or_b32 v138, v140, 8, v137
	v_lshrrev_b32_e32 v64, 11, v64
	v_and_or_b32 v64, v64, s9, v134
	v_lshl_or_b32 v140, v64, 14, v140
	v_mul_f32_e32 v64, v113, v129
	v_mul_f32_e32 v113, v97, v129
	v_ashrrev_i32_e32 v141, 31, v140
	v_lshlrev_b64 v[142:143], 7, v[140:141]
	v_lshl_add_u64 v[142:143], v[132:133], 0, v[142:143]
	v_mul_f32_e32 v97, v149, v113
	v_fma_f32 v97, v148, v64, -v97
	v_mul_f32_e32 v113, v148, v113
	v_fmac_f32_e32 v113, v149, v64
	v_cvt_pk_bf16_f32 v64, v97, s0
	global_store_short v[142:143], v64, off
	v_cvt_pk_bf16_f32 v64, v113, s0
	global_store_short v[142:143], v64, off offset:64
	v_mul_f32_e32 v64, v81, v129
	v_mul_f32_e32 v81, v149, v65
	v_mul_f32_e32 v129, v148, v65
	v_fma_f32 v81, v148, v64, -v81
	v_fmac_f32_e32 v129, v149, v64
	v_or_b32_e32 v64, 0x2000, v140
	v_ashrrev_i32_e32 v65, 31, v64
	v_lshlrev_b64 v[64:65], 7, v[64:65]
	v_cvt_pk_bf16_f32 v138, v81, s0
	v_lshl_add_u64 v[64:65], v[132:133], 0, v[64:65]
	global_store_short v[64:65], v138, off
	v_cvt_pk_bf16_f32 v138, v129, s0
	global_store_short v[64:65], v138, off offset:64
	v_add_u32_e32 v138, 2, v136
	v_and_b32_e32 v139, 0x1ffe, v138
	v_lshl_or_b32 v64, v139, 8, v137
	v_lshrrev_b32_e32 v138, 11, v138
	v_and_or_b32 v138, v138, s9, v134
	v_lshl_or_b32 v138, v138, 14, v139
	v_mul_f32_e32 v139, v114, v130
	v_mul_f32_e32 v114, v98, v130
	v_mul_f32_e32 v98, v151, v114
	v_mul_f32_e32 v114, v150, v114
	v_fma_f32 v98, v150, v139, -v98
	v_fmac_f32_e32 v114, v151, v139
	v_ashrrev_i32_e32 v139, 31, v138
	v_lshlrev_b64 v[140:141], 7, v[138:139]
	v_lshl_add_u64 v[140:141], v[132:133], 0, v[140:141]
	v_cvt_pk_bf16_f32 v139, v114, s0
	global_store_short v[140:141], v139, off offset:64
	v_mul_f32_e32 v139, v82, v130
	v_mul_f32_e32 v82, v151, v66
	v_fma_f32 v82, v150, v139, -v82
	v_mul_f32_e32 v130, v150, v66
	v_or_b32_e32 v64, 0x2000, v138
	v_fmac_f32_e32 v130, v151, v139
	v_ashrrev_i32_e32 v65, 31, v64
	v_lshlrev_b64 v[64:65], 7, v[64:65]
	v_cvt_pk_bf16_f32 v66, v82, s0
	v_lshl_add_u64 v[64:65], v[132:133], 0, v[64:65]
	global_store_short v[64:65], v66, off
	v_cvt_pk_bf16_f32 v66, v130, s0
	global_store_short v[64:65], v66, off offset:64
	v_add_u32_e32 v66, 3, v136
	v_cvt_pk_bf16_f32 v142, v98, s0
	v_and_b32_e32 v138, 0x1fff, v66
	global_store_short v[140:141], v142, off
	v_lshl_or_b32 v64, v138, 8, v137
	v_lshrrev_b32_e32 v66, 11, v66
	v_and_or_b32 v66, v66, s9, v134
	v_lshl_or_b32 v138, v66, 14, v138
	v_mul_f32_e32 v66, v115, v131
	v_mul_f32_e32 v115, v99, v131
	v_ashrrev_i32_e32 v139, 31, v138
	v_lshlrev_b64 v[140:141], 7, v[138:139]
	v_lshl_add_u64 v[140:141], v[132:133], 0, v[140:141]
	v_mul_f32_e32 v99, v153, v115
	v_fma_f32 v99, v152, v66, -v99
	v_mul_f32_e32 v115, v152, v115
	v_fmac_f32_e32 v115, v153, v66
	v_cvt_pk_bf16_f32 v66, v99, s0
	global_store_short v[140:141], v66, off
	v_cvt_pk_bf16_f32 v66, v115, s0
	global_store_short v[140:141], v66, off offset:64
	v_mul_f32_e32 v66, v83, v131
	v_mul_f32_e32 v83, v153, v67
	v_fma_f32 v83, v152, v66, -v83
	v_mul_f32_e32 v131, v152, v67
	v_or_b32_e32 v64, 0x2000, v138
	v_fmac_f32_e32 v131, v153, v66
	v_ashrrev_i32_e32 v65, 31, v64
	v_lshlrev_b64 v[64:65], 7, v[64:65]
	v_cvt_pk_bf16_f32 v66, v83, s0
	v_lshl_add_u64 v[64:65], v[132:133], 0, v[64:65]
	global_store_short v[64:65], v66, off
	v_cvt_pk_bf16_f32 v66, v131, s0
	global_store_short v[64:65], v66, off offset:64
	v_or_b32_e32 v64, 8, v144
	v_add_u32_e32 v140, s76, v64
	v_and_b32_e32 v141, 0x1ffc, v140
	v_lshl_or_b32 v138, v141, 8, v137
	v_lshl_add_u32 v64, v64, 2, s8
	ds_read_b128 v[64:67], v64
	v_lshrrev_b32_e32 v140, 11, v140
	v_and_or_b32 v140, v140, s9, v134
	v_lshl_or_b32 v140, v140, 14, v141
	s_waitcnt lgkmcnt(0)
; DI u16 f2bf(float a) { return (u16)(pack2(a, 0.f) & 0xffffu); }
; DI int crow(int reg, int g) { return (reg & 3) + 8 * (reg >> 2) + 4 * g; }
; template <bool TR>
; DI void gemm_in_tile(const P& p, int l, int id, char* smem) {
;     ...
; #pragma unroll
;     for (int rb = 0; rb < 2; ++rb) {
; #pragma unroll
;       for (int reg = 0; reg < 16; ++reg) {
;         if ((reg & 7) == 0) asm volatile("" ::: "memory");
;         const int rl = 64 * wr + 32 * rb + crow(reg, g);
;         const int tok = m0 + rl;
;         const float rs = rs_s[rl] * qs;
;         const int pos = tok & 8191, b = tok >> 13;
;         const float2 cs = p.rope[pos * 32 + li];
; #pragma unroll
;         for (int c = 0; c < 2; ++c) {
;           const float x1 = acc[rb][2 * c][reg] * rs, x2 = acc[rb][2 * c + 1][reg] * rs;
;           const float o1 = x1 * cs.x - x2 * cs.y, o2 = x2 * cs.x + x1 * cs.y;
;           const size_t base = ((size_t)(((b * 4 + h) * 2 + c) * SEQ + pos)) * 64;
;           dst[base + li] = f2bf(o1);
;           dst[base + 32 + li] = f2bf(o2);
;           if (c == 0) kl0 = fmaxf(kl0, o1 * o1 + o2 * o2); else kl1 = fmaxf(kl1, o1 * o1 + o2 * o2);
;         }
	v_mul_f32_e32 v64, v135, v64
	v_mul_f32_e32 v141, v116, v64
	v_mul_f32_e32 v116, v100, v64
	v_mul_f32_e32 v66, v135, v66
	v_mul_f32_e32 v100, v155, v116
	v_mul_f32_e32 v116, v154, v116
	v_fma_f32 v100, v154, v141, -v100
	v_fmac_f32_e32 v116, v155, v141
	v_ashrrev_i32_e32 v141, 31, v140
	v_lshlrev_b64 v[142:143], 7, v[140:141]
	v_lshl_add_u64 v[142:143], v[132:133], 0, v[142:143]
	v_cvt_pk_bf16_f32 v141, v116, s0
	global_store_short v[142:143], v141, off offset:64
	v_mul_f32_e32 v141, v84, v64
	v_mul_f32_e32 v64, v68, v64
	v_mul_f32_e32 v68, v155, v64
	v_fma_f32 v68, v154, v141, -v68
	v_mul_f32_e32 v84, v154, v64
	v_or_b32_e32 v138, 0x2000, v140
	v_fmac_f32_e32 v84, v155, v141
	v_ashrrev_i32_e32 v139, 31, v138
	v_lshlrev_b64 v[138:139], 7, v[138:139]
	v_cvt_pk_bf16_f32 v64, v68, s0
	v_lshl_add_u64 v[138:139], v[132:133], 0, v[138:139]
	global_store_short v[138:139], v64, off
	v_cvt_pk_bf16_f32 v64, v84, s0
	global_store_short v[138:139], v64, off offset:64
	v_add_u32_e32 v138, 9, v136
	v_cvt_pk_bf16_f32 v145, v100, s0
	v_and_b32_e32 v139, 0x1ffd, v138
	global_store_short v[142:143], v145, off
	v_lshl_or_b32 v64, v139, 8, v137
	v_mul_f32_e32 v142, v135, v65
	v_lshrrev_b32_e32 v138, 11, v138
	v_and_or_b32 v138, v138, s9, v134
	v_lshl_or_b32 v138, v138, 14, v139
	v_mul_f32_e32 v139, v117, v142
	v_mul_f32_e32 v117, v101, v142
	v_mul_f32_e32 v101, v157, v117
	v_mul_f32_e32 v117, v156, v117
	v_fma_f32 v101, v156, v139, -v101
	v_fmac_f32_e32 v117, v157, v139
	v_ashrrev_i32_e32 v139, 31, v138
	v_lshlrev_b64 v[140:141], 7, v[138:139]
	v_lshl_add_u64 v[140:141], v[132:133], 0, v[140:141]
	v_cvt_pk_bf16_f32 v139, v117, s0
	global_store_short v[140:141], v139, off offset:64
	v_mul_f32_e32 v139, v85, v142
	v_mul_f32_e32 v85, v69, v142
	v_mul_f32_e32 v69, v157, v85
	v_fma_f32 v69, v156, v139, -v69
	v_mul_f32_e32 v85, v156, v85
	v_or_b32_e32 v64, 0x2000, v138
	v_fmac_f32_e32 v85, v157, v139
	v_ashrrev_i32_e32 v65, 31, v64
	v_lshlrev_b64 v[64:65], 7, v[64:65]
	v_cvt_pk_bf16_f32 v138, v69, s0
	v_lshl_add_u64 v[64:65], v[132:133], 0, v[64:65]
	global_store_short v[64:65], v138, off
	v_cvt_pk_bf16_f32 v138, v85, s0
	global_store_short v[64:65], v138, off offset:64
	v_add_u32_e32 v138, 10, v136
	v_cvt_pk_bf16_f32 v143, v101, s0
	v_and_b32_e32 v139, 0x1ffe, v138
	global_store_short v[140:141], v143, off
	v_lshl_or_b32 v64, v139, 8, v137
	v_lshrrev_b32_e32 v138, 11, v138
	v_and_or_b32 v138, v138, s9, v134
	v_lshl_or_b32 v138, v138, 14, v139
	v_mul_f32_e32 v139, v118, v66
	v_mul_f32_e32 v118, v102, v66
	v_mul_f32_e32 v102, v159, v118
	v_mul_f32_e32 v118, v158, v118
	v_fma_f32 v102, v158, v139, -v102
	v_fmac_f32_e32 v118, v159, v139
	v_ashrrev_i32_e32 v139, 31, v138
	v_lshlrev_b64 v[140:141], 7, v[138:139]
	v_lshl_add_u64 v[140:141], v[132:133], 0, v[140:141]
	v_cvt_pk_bf16_f32 v139, v118, s0
	global_store_short v[140:141], v139, off offset:64
	v_mul_f32_e32 v139, v86, v66
	v_mul_f32_e32 v66, v70, v66
	v_mul_f32_e32 v70, v159, v66
	v_fma_f32 v70, v158, v139, -v70
	v_mul_f32_e32 v86, v158, v66
	v_or_b32_e32 v64, 0x2000, v138
	v_fmac_f32_e32 v86, v159, v139
	v_ashrrev_i32_e32 v65, 31, v64
	v_lshlrev_b64 v[64:65], 7, v[64:65]
	v_cvt_pk_bf16_f32 v66, v70, s0
	v_lshl_add_u64 v[64:65], v[132:133], 0, v[64:65]
	global_store_short v[64:65], v66, off
	v_cvt_pk_bf16_f32 v66, v86, s0
	v_cvt_pk_bf16_f32 v142, v102, s0
	global_store_short v[64:65], v66, off offset:64
	v_add_u32_e32 v66, 11, v136
	global_store_short v[140:141], v142, off
	v_mul_f32_e32 v140, v135, v67
	v_and_b32_e32 v67, 0x1fff, v66
	v_lshl_or_b32 v64, v67, 8, v137
	v_lshrrev_b32_e32 v66, 11, v66
	v_and_or_b32 v66, v66, s9, v134
	v_lshl_or_b32 v66, v66, 14, v67
	v_mul_f32_e32 v67, v119, v140
	v_mul_f32_e32 v119, v103, v140
	v_mul_f32_e32 v103, v161, v119
	v_mul_f32_e32 v119, v160, v119
	v_fma_f32 v103, v160, v67, -v103
	v_fmac_f32_e32 v119, v161, v67
	v_ashrrev_i32_e32 v67, 31, v66
	v_lshlrev_b64 v[138:139], 7, v[66:67]
	v_lshl_add_u64 v[138:139], v[132:133], 0, v[138:139]
	v_cvt_pk_bf16_f32 v67, v119, s0
	global_store_short v[138:139], v67, off offset:64
	v_mul_f32_e32 v67, v87, v140
	v_mul_f32_e32 v87, v71, v140
	v_mul_f32_e32 v71, v161, v87
	v_fma_f32 v71, v160, v67, -v71
	v_mul_f32_e32 v87, v160, v87
	v_or_b32_e32 v64, 0x2000, v66
	v_fmac_f32_e32 v87, v161, v67
	v_ashrrev_i32_e32 v65, 31, v64
	v_lshlrev_b64 v[64:65], 7, v[64:65]
	v_cvt_pk_bf16_f32 v66, v71, s0
	v_lshl_add_u64 v[64:65], v[132:133], 0, v[64:65]
	global_store_short v[64:65], v66, off
	v_cvt_pk_bf16_f32 v66, v87, s0
	global_store_short v[64:65], v66, off offset:64
	v_or_b32_e32 v64, 16, v144
	v_cvt_pk_bf16_f32 v141, v103, s0
	v_add_u32_e32 v140, s76, v64
	global_store_short v[138:139], v141, off
	v_and_b32_e32 v141, 0x1ffc, v140
	v_lshl_or_b32 v138, v141, 8, v137
	v_lshl_add_u32 v64, v64, 2, s8
	ds_read_b128 v[64:67], v64
	v_lshrrev_b32_e32 v140, 11, v140
	v_and_or_b32 v140, v140, s9, v134
	v_lshl_or_b32 v140, v140, 14, v141
	s_waitcnt lgkmcnt(0)
; DI u16 f2bf(float a) { return (u16)(pack2(a, 0.f) & 0xffffu); }
; DI int crow(int reg, int g) { return (reg & 3) + 8 * (reg >> 2) + 4 * g; }
; template <bool TR>
; DI void gemm_in_tile(const P& p, int l, int id, char* smem) {
;     ...
; #pragma unroll
;     for (int rb = 0; rb < 2; ++rb) {
; #pragma unroll
;       for (int reg = 0; reg < 16; ++reg) {
;         if ((reg & 7) == 0) asm volatile("" ::: "memory");
;         const int rl = 64 * wr + 32 * rb + crow(reg, g);
;         const int tok = m0 + rl;
;         const float rs = rs_s[rl] * qs;
;         const int pos = tok & 8191, b = tok >> 13;
;         const float2 cs = p.rope[pos * 32 + li];
; #pragma unroll
;         for (int c = 0; c < 2; ++c) {
;           const float x1 = acc[rb][2 * c][reg] * rs, x2 = acc[rb][2 * c + 1][reg] * rs;
;           const float o1 = x1 * cs.x - x2 * cs.y, o2 = x2 * cs.x + x1 * cs.y;
;           const size_t base = ((size_t)(((b * 4 + h) * 2 + c) * SEQ + pos)) * 64;
;           dst[base + li] = f2bf(o1);
;           dst[base + 32 + li] = f2bf(o2);
;           if (c == 0) kl0 = fmaxf(kl0, o1 * o1 + o2 * o2); else kl1 = fmaxf(kl1, o1 * o1 + o2 * o2);
;         }
	v_mul_f32_e32 v64, v135, v64
	v_mul_f32_e32 v141, v120, v64
	v_mul_f32_e32 v120, v104, v64
	v_mul_f32_e32 v66, v135, v66
	v_mul_f32_e32 v104, v163, v120
	v_mul_f32_e32 v120, v162, v120
	v_fma_f32 v104, v162, v141, -v104
	v_fmac_f32_e32 v120, v163, v141
	v_ashrrev_i32_e32 v141, 31, v140
	v_lshlrev_b64 v[142:143], 7, v[140:141]
	v_lshl_add_u64 v[142:143], v[132:133], 0, v[142:143]
	v_cvt_pk_bf16_f32 v141, v120, s0
	global_store_short v[142:143], v141, off offset:64
	v_mul_f32_e32 v141, v88, v64
	v_mul_f32_e32 v64, v72, v64
	v_mul_f32_e32 v72, v163, v64
	v_fma_f32 v72, v162, v141, -v72
	v_mul_f32_e32 v88, v162, v64
	v_or_b32_e32 v138, 0x2000, v140
	v_fmac_f32_e32 v88, v163, v141
	v_ashrrev_i32_e32 v139, 31, v138
	v_lshlrev_b64 v[138:139], 7, v[138:139]
	v_cvt_pk_bf16_f32 v64, v72, s0
	v_lshl_add_u64 v[138:139], v[132:133], 0, v[138:139]
	global_store_short v[138:139], v64, off
	v_cvt_pk_bf16_f32 v64, v88, s0
	global_store_short v[138:139], v64, off offset:64
	v_add_u32_e32 v138, 17, v136
	v_cvt_pk_bf16_f32 v145, v104, s0
	v_and_b32_e32 v139, 0x1ffd, v138
	global_store_short v[142:143], v145, off
	v_lshl_or_b32 v64, v139, 8, v137
	v_mul_f32_e32 v142, v135, v65
	v_lshrrev_b32_e32 v138, 11, v138
	v_and_or_b32 v138, v138, s9, v134
	v_lshl_or_b32 v138, v138, 14, v139
	v_mul_f32_e32 v139, v121, v142
	v_mul_f32_e32 v121, v105, v142
	v_mul_f32_e32 v105, v165, v121
	v_mul_f32_e32 v121, v164, v121
	v_fma_f32 v105, v164, v139, -v105
	v_fmac_f32_e32 v121, v165, v139
	v_ashrrev_i32_e32 v139, 31, v138
	v_lshlrev_b64 v[140:141], 7, v[138:139]
	v_lshl_add_u64 v[140:141], v[132:133], 0, v[140:141]
	v_cvt_pk_bf16_f32 v139, v121, s0
	global_store_short v[140:141], v139, off offset:64
	v_mul_f32_e32 v139, v89, v142
	v_mul_f32_e32 v89, v73, v142
	v_mul_f32_e32 v73, v165, v89
	v_fma_f32 v73, v164, v139, -v73
	v_mul_f32_e32 v89, v164, v89
	v_or_b32_e32 v64, 0x2000, v138
	v_fmac_f32_e32 v89, v165, v139
	v_ashrrev_i32_e32 v65, 31, v64
	v_lshlrev_b64 v[64:65], 7, v[64:65]
	v_cvt_pk_bf16_f32 v138, v73, s0
	v_lshl_add_u64 v[64:65], v[132:133], 0, v[64:65]
	global_store_short v[64:65], v138, off
	v_cvt_pk_bf16_f32 v138, v89, s0
	global_store_short v[64:65], v138, off offset:64
	v_add_u32_e32 v138, 18, v136
	v_cvt_pk_bf16_f32 v143, v105, s0
	v_and_b32_e32 v139, 0x1ffe, v138
	global_store_short v[140:141], v143, off
	v_lshl_or_b32 v64, v139, 8, v137
	v_lshrrev_b32_e32 v138, 11, v138
	v_and_or_b32 v138, v138, s9, v134
	v_lshl_or_b32 v138, v138, 14, v139
	v_mul_f32_e32 v139, v122, v66
	v_mul_f32_e32 v122, v106, v66
	v_mul_f32_e32 v106, v167, v122
	v_mul_f32_e32 v122, v166, v122
	v_fma_f32 v106, v166, v139, -v106
	v_fmac_f32_e32 v122, v167, v139
	v_ashrrev_i32_e32 v139, 31, v138
	v_lshlrev_b64 v[140:141], 7, v[138:139]
	v_lshl_add_u64 v[140:141], v[132:133], 0, v[140:141]
	v_cvt_pk_bf16_f32 v139, v122, s0
	global_store_short v[140:141], v139, off offset:64
	v_mul_f32_e32 v139, v90, v66
	v_mul_f32_e32 v66, v74, v66
	v_mul_f32_e32 v74, v167, v66
	v_fma_f32 v74, v166, v139, -v74
	v_mul_f32_e32 v90, v166, v66
	v_or_b32_e32 v64, 0x2000, v138
	v_fmac_f32_e32 v90, v167, v139
	v_ashrrev_i32_e32 v65, 31, v64
	v_lshlrev_b64 v[64:65], 7, v[64:65]
	v_cvt_pk_bf16_f32 v66, v74, s0
	v_lshl_add_u64 v[64:65], v[132:133], 0, v[64:65]
	global_store_short v[64:65], v66, off
	v_cvt_pk_bf16_f32 v66, v90, s0
	v_cvt_pk_bf16_f32 v142, v106, s0
	global_store_short v[64:65], v66, off offset:64
	v_add_u32_e32 v66, 19, v136
	global_store_short v[140:141], v142, off
	v_mul_f32_e32 v140, v135, v67
	v_and_b32_e32 v67, 0x1fff, v66
	v_lshl_or_b32 v64, v67, 8, v137
	v_lshrrev_b32_e32 v66, 11, v66
	v_and_or_b32 v66, v66, s9, v134
	v_lshl_or_b32 v66, v66, 14, v67
	v_mul_f32_e32 v67, v123, v140
	v_mul_f32_e32 v123, v107, v140
	v_mul_f32_e32 v107, v169, v123
	v_mul_f32_e32 v123, v168, v123
	v_fma_f32 v107, v168, v67, -v107
	v_fmac_f32_e32 v123, v169, v67
	v_ashrrev_i32_e32 v67, 31, v66
	v_lshlrev_b64 v[138:139], 7, v[66:67]
	v_lshl_add_u64 v[138:139], v[132:133], 0, v[138:139]
	v_cvt_pk_bf16_f32 v67, v123, s0
	global_store_short v[138:139], v67, off offset:64
	v_mul_f32_e32 v67, v91, v140
	v_mul_f32_e32 v91, v75, v140
	v_mul_f32_e32 v75, v169, v91
	v_fma_f32 v75, v168, v67, -v75
	v_mul_f32_e32 v91, v168, v91
	v_or_b32_e32 v64, 0x2000, v66
	v_fmac_f32_e32 v91, v169, v67
	v_ashrrev_i32_e32 v65, 31, v64
	v_lshlrev_b64 v[64:65], 7, v[64:65]
	v_cvt_pk_bf16_f32 v66, v75, s0
	v_lshl_add_u64 v[64:65], v[132:133], 0, v[64:65]
	global_store_short v[64:65], v66, off
	v_cvt_pk_bf16_f32 v66, v91, s0
	global_store_short v[64:65], v66, off offset:64
	v_or_b32_e32 v64, 24, v144
	v_cvt_pk_bf16_f32 v141, v107, s0
	v_add_u32_e32 v140, s76, v64
	global_store_short v[138:139], v141, off
	v_and_b32_e32 v141, 0x1ffc, v140
	v_lshl_or_b32 v138, v141, 8, v137
	v_lshl_add_u32 v64, v64, 2, s8
	ds_read_b128 v[64:67], v64
	v_lshrrev_b32_e32 v140, 11, v140
	v_and_or_b32 v140, v140, s9, v134
	v_lshl_or_b32 v140, v140, 14, v141
	s_waitcnt lgkmcnt(0)
; DI u16 f2bf(float a) { return (u16)(pack2(a, 0.f) & 0xffffu); }
; DI int crow(int reg, int g) { return (reg & 3) + 8 * (reg >> 2) + 4 * g; }
; template <bool TR>
; DI void gemm_in_tile(const P& p, int l, int id, char* smem) {
;     ...
; #pragma unroll
;     for (int rb = 0; rb < 2; ++rb) {
; #pragma unroll
;       for (int reg = 0; reg < 16; ++reg) {
;         if ((reg & 7) == 0) asm volatile("" ::: "memory");
;         const int rl = 64 * wr + 32 * rb + crow(reg, g);
;         const int tok = m0 + rl;
;         const float rs = rs_s[rl] * qs;
;         const int pos = tok & 8191, b = tok >> 13;
;         const float2 cs = p.rope[pos * 32 + li];
; #pragma unroll
;         for (int c = 0; c < 2; ++c) {
;           const float x1 = acc[rb][2 * c][reg] * rs, x2 = acc[rb][2 * c + 1][reg] * rs;
;           const float o1 = x1 * cs.x - x2 * cs.y, o2 = x2 * cs.x + x1 * cs.y;
;           const size_t base = ((size_t)(((b * 4 + h) * 2 + c) * SEQ + pos)) * 64;
;           dst[base + li] = f2bf(o1);
;           dst[base + 32 + li] = f2bf(o2);
;           if (c == 0) kl0 = fmaxf(kl0, o1 * o1 + o2 * o2); else kl1 = fmaxf(kl1, o1 * o1 + o2 * o2);
;         }
	v_mul_f32_e32 v64, v135, v64
	v_mul_f32_e32 v141, v124, v64
	v_mul_f32_e32 v124, v108, v64
	v_mul_f32_e32 v66, v135, v66
	v_mul_f32_e32 v108, v171, v124
	v_mul_f32_e32 v124, v170, v124
	v_fma_f32 v108, v170, v141, -v108
	v_fmac_f32_e32 v124, v171, v141
	v_ashrrev_i32_e32 v141, 31, v140
	v_lshlrev_b64 v[142:143], 7, v[140:141]
	v_lshl_add_u64 v[142:143], v[132:133], 0, v[142:143]
	v_cvt_pk_bf16_f32 v141, v124, s0
	global_store_short v[142:143], v141, off offset:64
	v_mul_f32_e32 v141, v92, v64
	v_mul_f32_e32 v64, v76, v64
	v_mul_f32_e32 v76, v171, v64
	v_fma_f32 v76, v170, v141, -v76
	v_mul_f32_e32 v92, v170, v64
	v_or_b32_e32 v138, 0x2000, v140
	v_fmac_f32_e32 v92, v171, v141
	v_ashrrev_i32_e32 v139, 31, v138
	v_lshlrev_b64 v[138:139], 7, v[138:139]
	v_cvt_pk_bf16_f32 v64, v76, s0
	v_lshl_add_u64 v[138:139], v[132:133], 0, v[138:139]
	global_store_short v[138:139], v64, off
	v_cvt_pk_bf16_f32 v64, v92, s0
	global_store_short v[138:139], v64, off offset:64
	v_add_u32_e32 v138, 25, v136
	v_cvt_pk_bf16_f32 v145, v108, s0
	v_and_b32_e32 v139, 0x1ffd, v138
	global_store_short v[142:143], v145, off
	v_lshl_or_b32 v64, v139, 8, v137
	v_mul_f32_e32 v142, v135, v65
	v_lshrrev_b32_e32 v138, 11, v138
	v_and_or_b32 v138, v138, s9, v134
	v_lshl_or_b32 v138, v138, 14, v139
	v_mul_f32_e32 v139, v125, v142
	v_mul_f32_e32 v125, v109, v142
	v_mul_f32_e32 v109, v173, v125
	v_mul_f32_e32 v125, v172, v125
	v_fma_f32 v109, v172, v139, -v109
	v_fmac_f32_e32 v125, v173, v139
	v_ashrrev_i32_e32 v139, 31, v138
	v_lshlrev_b64 v[140:141], 7, v[138:139]
	v_lshl_add_u64 v[140:141], v[132:133], 0, v[140:141]
	v_cvt_pk_bf16_f32 v139, v125, s0
	global_store_short v[140:141], v139, off offset:64
	v_mul_f32_e32 v139, v93, v142
	v_mul_f32_e32 v93, v77, v142
	v_mul_f32_e32 v77, v173, v93
	v_fma_f32 v77, v172, v139, -v77
	v_mul_f32_e32 v93, v172, v93
	v_or_b32_e32 v64, 0x2000, v138
	v_fmac_f32_e32 v93, v173, v139
	v_ashrrev_i32_e32 v65, 31, v64
	v_lshlrev_b64 v[64:65], 7, v[64:65]
	v_cvt_pk_bf16_f32 v138, v77, s0
	v_lshl_add_u64 v[64:65], v[132:133], 0, v[64:65]
	global_store_short v[64:65], v138, off
	v_cvt_pk_bf16_f32 v138, v93, s0
	global_store_short v[64:65], v138, off offset:64
	v_add_u32_e32 v138, 26, v136
	v_cvt_pk_bf16_f32 v143, v109, s0
	v_and_b32_e32 v139, 0x1ffe, v138
	global_store_short v[140:141], v143, off
	v_lshl_or_b32 v64, v139, 8, v137
	v_lshrrev_b32_e32 v138, 11, v138
	v_and_or_b32 v138, v138, s9, v134
	v_lshl_or_b32 v138, v138, 14, v139
	v_mul_f32_e32 v139, v126, v66
	v_mul_f32_e32 v126, v110, v66
	v_mul_f32_e32 v110, v175, v126
	v_mul_f32_e32 v126, v174, v126
	v_fma_f32 v110, v174, v139, -v110
	v_fmac_f32_e32 v126, v175, v139
	v_ashrrev_i32_e32 v139, 31, v138
	v_lshlrev_b64 v[140:141], 7, v[138:139]
	v_lshl_add_u64 v[140:141], v[132:133], 0, v[140:141]
	v_cvt_pk_bf16_f32 v139, v126, s0
	global_store_short v[140:141], v139, off offset:64
	v_mul_f32_e32 v139, v94, v66
	v_mul_f32_e32 v66, v78, v66
	v_mul_f32_e32 v78, v175, v66
	v_fma_f32 v78, v174, v139, -v78
	v_mul_f32_e32 v94, v174, v66
	v_or_b32_e32 v64, 0x2000, v138
	v_fmac_f32_e32 v94, v175, v139
	v_ashrrev_i32_e32 v65, 31, v64
	v_lshlrev_b64 v[64:65], 7, v[64:65]
	v_cvt_pk_bf16_f32 v66, v78, s0
	v_lshl_add_u64 v[64:65], v[132:133], 0, v[64:65]
	global_store_short v[64:65], v66, off
	v_cvt_pk_bf16_f32 v66, v94, s0
	v_cvt_pk_bf16_f32 v142, v110, s0
	global_store_short v[64:65], v66, off offset:64
	v_add_u32_e32 v66, 27, v136
	global_store_short v[140:141], v142, off
	v_mul_f32_e32 v140, v135, v67
	v_and_b32_e32 v67, 0x1fff, v66
	v_lshl_or_b32 v64, v67, 8, v137
	v_lshrrev_b32_e32 v66, 11, v66
	v_and_or_b32 v66, v66, s9, v134
	v_lshl_or_b32 v66, v66, 14, v67
	v_mul_f32_e32 v67, v127, v140
	v_mul_f32_e32 v127, v111, v140
	v_mul_f32_e32 v111, v221, v127
	v_mul_f32_e32 v127, v220, v127
	v_fma_f32 v111, v220, v67, -v111
	v_fmac_f32_e32 v127, v221, v67
	v_ashrrev_i32_e32 v67, 31, v66
	v_lshlrev_b64 v[138:139], 7, v[66:67]
	v_lshl_add_u64 v[138:139], v[132:133], 0, v[138:139]
	v_cvt_pk_bf16_f32 v67, v127, s0
	global_store_short v[138:139], v67, off offset:64
	v_mul_f32_e32 v67, v95, v140
	v_mul_f32_e32 v95, v79, v140
	v_mul_f32_e32 v79, v221, v95
	v_fma_f32 v79, v220, v67, -v79
	v_mul_f32_e32 v95, v220, v95
	v_or_b32_e32 v64, 0x2000, v66
	v_fmac_f32_e32 v95, v221, v67
	v_ashrrev_i32_e32 v65, 31, v64
	v_lshlrev_b64 v[64:65], 7, v[64:65]
	v_cvt_pk_bf16_f32 v66, v79, s0
	v_lshl_add_u64 v[64:65], v[132:133], 0, v[64:65]
	global_store_short v[64:65], v66, off
	v_cvt_pk_bf16_f32 v66, v95, s0
	global_store_short v[64:65], v66, off offset:64
	v_or_b32_e32 v64, 32, v144
	v_cvt_pk_bf16_f32 v141, v111, s0
	v_add_u32_e32 v140, s76, v64
	global_store_short v[138:139], v141, off
	v_and_b32_e32 v141, 0x1ffc, v140
	v_lshl_or_b32 v138, v141, 8, v137
	v_lshl_add_u32 v64, v64, 2, s8
	ds_read_b128 v[64:67], v64
	v_lshrrev_b32_e32 v140, 11, v140
	v_and_or_b32 v140, v140, s9, v134
	v_lshl_or_b32 v140, v140, 14, v141
	s_waitcnt lgkmcnt(0)
; DI u16 f2bf(float a) { return (u16)(pack2(a, 0.f) & 0xffffu); }
; DI int crow(int reg, int g) { return (reg & 3) + 8 * (reg >> 2) + 4 * g; }
; template <bool TR>
; DI void gemm_in_tile(const P& p, int l, int id, char* smem) {
;     ...
; #pragma unroll
;     for (int rb = 0; rb < 2; ++rb) {
; #pragma unroll
;       for (int reg = 0; reg < 16; ++reg) {
;         if ((reg & 7) == 0) asm volatile("" ::: "memory");
;         const int rl = 64 * wr + 32 * rb + crow(reg, g);
;         const int tok = m0 + rl;
;         const float rs = rs_s[rl] * qs;
;         const int pos = tok & 8191, b = tok >> 13;
;         const float2 cs = p.rope[pos * 32 + li];
; #pragma unroll
;         for (int c = 0; c < 2; ++c) {
;           const float x1 = acc[rb][2 * c][reg] * rs, x2 = acc[rb][2 * c + 1][reg] * rs;
;           const float o1 = x1 * cs.x - x2 * cs.y, o2 = x2 * cs.x + x1 * cs.y;
;           const size_t base = ((size_t)(((b * 4 + h) * 2 + c) * SEQ + pos)) * 64;
;           dst[base + li] = f2bf(o1);
;           dst[base + 32 + li] = f2bf(o2);
;           if (c == 0) kl0 = fmaxf(kl0, o1 * o1 + o2 * o2); else kl1 = fmaxf(kl1, o1 * o1 + o2 * o2);
;         }
	v_mul_f32_e32 v64, v135, v64
	v_mul_f32_e32 v141, v48, v64
	v_mul_f32_e32 v48, v32, v64
	v_mul_f32_e32 v0, v0, v64
	v_mul_f32_e32 v65, v135, v65
	v_mul_f32_e32 v1, v1, v65
	v_mul_f32_e32 v66, v135, v66
	v_mul_f32_e32 v2, v2, v66
	v_mul_f32_e32 v67, v135, v67
	v_mul_f32_e32 v3, v3, v67
	v_mul_f32_e32 v32, v223, v48
	v_mul_f32_e32 v48, v222, v48
	v_fma_f32 v32, v222, v141, -v32
	v_fmac_f32_e32 v48, v223, v141
	v_ashrrev_i32_e32 v141, 31, v140
	v_lshlrev_b64 v[142:143], 7, v[140:141]
	v_lshl_add_u64 v[142:143], v[132:133], 0, v[142:143]
	v_cvt_pk_bf16_f32 v141, v48, s0
	global_store_short v[142:143], v141, off offset:64
	v_mul_f32_e32 v141, v16, v64
	v_mul_f32_e32 v16, v223, v0
	v_fma_f32 v16, v222, v141, -v16
	v_mul_f32_e32 v64, v222, v0
	v_or_b32_e32 v138, 0x2000, v140
	v_fmac_f32_e32 v64, v223, v141
	v_ashrrev_i32_e32 v139, 31, v138
	v_lshlrev_b64 v[138:139], 7, v[138:139]
	v_cvt_pk_bf16_f32 v0, v16, s0
	v_lshl_add_u64 v[138:139], v[132:133], 0, v[138:139]
	global_store_short v[138:139], v0, off
	v_cvt_pk_bf16_f32 v0, v64, s0
	global_store_short v[138:139], v0, off offset:64
	v_add_u32_e32 v0, 33, v136
	v_cvt_pk_bf16_f32 v145, v32, s0
	v_and_b32_e32 v140, 0x1ffd, v0
	global_store_short v[142:143], v145, off
	v_lshl_or_b32 v138, v140, 8, v137
	v_lshrrev_b32_e32 v0, 11, v0
	v_and_or_b32 v0, v0, s9, v134
	v_lshl_or_b32 v140, v0, 14, v140
	v_mul_f32_e32 v0, v49, v65
	v_mul_f32_e32 v49, v33, v65
	v_ashrrev_i32_e32 v141, 31, v140
	v_lshlrev_b64 v[142:143], 7, v[140:141]
	v_lshl_add_u64 v[142:143], v[132:133], 0, v[142:143]
	v_mul_f32_e32 v33, v225, v49
	v_fma_f32 v33, v224, v0, -v33
	v_mul_f32_e32 v49, v224, v49
	v_fmac_f32_e32 v49, v225, v0
	v_cvt_pk_bf16_f32 v0, v33, s0
	global_store_short v[142:143], v0, off
	v_cvt_pk_bf16_f32 v0, v49, s0
	global_store_short v[142:143], v0, off offset:64
	v_mul_f32_e32 v0, v17, v65
	v_mul_f32_e32 v17, v225, v1
	v_mul_f32_e32 v65, v224, v1
	v_fma_f32 v17, v224, v0, -v17
	v_fmac_f32_e32 v65, v225, v0
	v_or_b32_e32 v0, 0x2000, v140
	v_ashrrev_i32_e32 v1, 31, v0
	v_lshlrev_b64 v[0:1], 7, v[0:1]
	v_cvt_pk_bf16_f32 v138, v17, s0
	v_lshl_add_u64 v[0:1], v[132:133], 0, v[0:1]
	global_store_short v[0:1], v138, off
	v_cvt_pk_bf16_f32 v138, v65, s0
	global_store_short v[0:1], v138, off offset:64
	v_add_u32_e32 v138, 34, v136
	v_and_b32_e32 v139, 0x1ffe, v138
	v_lshl_or_b32 v0, v139, 8, v137
	v_lshrrev_b32_e32 v138, 11, v138
	v_and_or_b32 v138, v138, s9, v134
	v_lshl_or_b32 v138, v138, 14, v139
	v_mul_f32_e32 v139, v50, v66
	v_mul_f32_e32 v50, v34, v66
	v_mul_f32_e32 v34, v227, v50
	v_mul_f32_e32 v50, v226, v50
	v_fma_f32 v34, v226, v139, -v34
	v_fmac_f32_e32 v50, v227, v139
	v_ashrrev_i32_e32 v139, 31, v138
	v_lshlrev_b64 v[140:141], 7, v[138:139]
	v_lshl_add_u64 v[140:141], v[132:133], 0, v[140:141]
	v_cvt_pk_bf16_f32 v139, v50, s0
	global_store_short v[140:141], v139, off offset:64
	v_mul_f32_e32 v139, v18, v66
	v_mul_f32_e32 v18, v227, v2
	v_fma_f32 v18, v226, v139, -v18
	v_mul_f32_e32 v66, v226, v2
	v_or_b32_e32 v0, 0x2000, v138
	v_fmac_f32_e32 v66, v227, v139
	v_ashrrev_i32_e32 v1, 31, v0
	v_lshlrev_b64 v[0:1], 7, v[0:1]
	v_cvt_pk_bf16_f32 v2, v18, s0
	v_lshl_add_u64 v[0:1], v[132:133], 0, v[0:1]
	global_store_short v[0:1], v2, off
	v_cvt_pk_bf16_f32 v2, v66, s0
	global_store_short v[0:1], v2, off offset:64
	v_add_u32_e32 v2, 35, v136
	v_cvt_pk_bf16_f32 v142, v34, s0
	v_and_b32_e32 v138, 0x1fff, v2
	global_store_short v[140:141], v142, off
	v_lshl_or_b32 v0, v138, 8, v137
	v_lshrrev_b32_e32 v2, 11, v2
	v_and_or_b32 v2, v2, s9, v134
	v_lshl_or_b32 v138, v2, 14, v138
	v_mul_f32_e32 v2, v51, v67
	v_mul_f32_e32 v51, v35, v67
	v_ashrrev_i32_e32 v139, 31, v138
	v_lshlrev_b64 v[140:141], 7, v[138:139]
	v_lshl_add_u64 v[140:141], v[132:133], 0, v[140:141]
	v_mul_f32_e32 v35, v229, v51
	v_fma_f32 v35, v228, v2, -v35
	v_mul_f32_e32 v51, v228, v51
	v_fmac_f32_e32 v51, v229, v2
	v_cvt_pk_bf16_f32 v2, v35, s0
	global_store_short v[140:141], v2, off
	v_cvt_pk_bf16_f32 v2, v51, s0
	global_store_short v[140:141], v2, off offset:64
	v_mul_f32_e32 v2, v19, v67
	v_mul_f32_e32 v19, v229, v3
	v_fma_f32 v19, v228, v2, -v19
	v_mul_f32_e32 v67, v228, v3
	v_or_b32_e32 v0, 0x2000, v138
	v_fmac_f32_e32 v67, v229, v2
	v_ashrrev_i32_e32 v1, 31, v0
	v_lshlrev_b64 v[0:1], 7, v[0:1]
	v_cvt_pk_bf16_f32 v2, v19, s0
	v_lshl_add_u64 v[0:1], v[132:133], 0, v[0:1]
	global_store_short v[0:1], v2, off
	v_cvt_pk_bf16_f32 v2, v67, s0
	global_store_short v[0:1], v2, off offset:64
	v_or_b32_e32 v0, 40, v144
	v_add_u32_e32 v140, s76, v0
	v_and_b32_e32 v141, 0x1ffc, v140
	v_lshl_or_b32 v138, v141, 8, v137
	v_lshl_add_u32 v0, v0, 2, s8
	ds_read_b128 v[0:3], v0
	v_lshrrev_b32_e32 v140, 11, v140
	v_and_or_b32 v140, v140, s9, v134
	v_lshl_or_b32 v140, v140, 14, v141
	s_waitcnt lgkmcnt(0)
; DI u16 f2bf(float a) { return (u16)(pack2(a, 0.f) & 0xffffu); }
; DI int crow(int reg, int g) { return (reg & 3) + 8 * (reg >> 2) + 4 * g; }
; template <bool TR>
; DI void gemm_in_tile(const P& p, int l, int id, char* smem) {
;     ...
; #pragma unroll
;     for (int rb = 0; rb < 2; ++rb) {
; #pragma unroll
;       for (int reg = 0; reg < 16; ++reg) {
;         if ((reg & 7) == 0) asm volatile("" ::: "memory");
;         const int rl = 64 * wr + 32 * rb + crow(reg, g);
;         const int tok = m0 + rl;
;         const float rs = rs_s[rl] * qs;
;         const int pos = tok & 8191, b = tok >> 13;
;         const float2 cs = p.rope[pos * 32 + li];
; #pragma unroll
;         for (int c = 0; c < 2; ++c) {
;           const float x1 = acc[rb][2 * c][reg] * rs, x2 = acc[rb][2 * c + 1][reg] * rs;
;           const float o1 = x1 * cs.x - x2 * cs.y, o2 = x2 * cs.x + x1 * cs.y;
;           const size_t base = ((size_t)(((b * 4 + h) * 2 + c) * SEQ + pos)) * 64;
;           dst[base + li] = f2bf(o1);
;           dst[base + 32 + li] = f2bf(o2);
;           if (c == 0) kl0 = fmaxf(kl0, o1 * o1 + o2 * o2); else kl1 = fmaxf(kl1, o1 * o1 + o2 * o2);
;         }
	v_mul_f32_e32 v0, v135, v0
	v_mul_f32_e32 v141, v52, v0
	v_mul_f32_e32 v52, v36, v0
	v_mul_f32_e32 v2, v135, v2
	v_mul_f32_e32 v36, v231, v52
	v_mul_f32_e32 v52, v230, v52
	v_fma_f32 v36, v230, v141, -v36
	v_fmac_f32_e32 v52, v231, v141
	v_ashrrev_i32_e32 v141, 31, v140
	v_lshlrev_b64 v[142:143], 7, v[140:141]
	v_lshl_add_u64 v[142:143], v[132:133], 0, v[142:143]
	v_cvt_pk_bf16_f32 v141, v52, s0
	global_store_short v[142:143], v141, off offset:64
	v_mul_f32_e32 v141, v20, v0
	v_mul_f32_e32 v0, v4, v0
	v_mul_f32_e32 v4, v231, v0
	v_fma_f32 v4, v230, v141, -v4
	v_mul_f32_e32 v20, v230, v0
	v_or_b32_e32 v138, 0x2000, v140
	v_fmac_f32_e32 v20, v231, v141
	v_ashrrev_i32_e32 v139, 31, v138
	v_lshlrev_b64 v[138:139], 7, v[138:139]
	v_cvt_pk_bf16_f32 v0, v4, s0
	v_lshl_add_u64 v[138:139], v[132:133], 0, v[138:139]
	global_store_short v[138:139], v0, off
	v_cvt_pk_bf16_f32 v0, v20, s0
	global_store_short v[138:139], v0, off offset:64
	v_add_u32_e32 v138, 41, v136
	v_cvt_pk_bf16_f32 v145, v36, s0
	v_and_b32_e32 v139, 0x1ffd, v138
	global_store_short v[142:143], v145, off
	v_lshl_or_b32 v0, v139, 8, v137
	v_mul_f32_e32 v142, v135, v1
	v_lshrrev_b32_e32 v138, 11, v138
	v_and_or_b32 v138, v138, s9, v134
	v_lshl_or_b32 v138, v138, 14, v139
	v_mul_f32_e32 v139, v53, v142
	v_mul_f32_e32 v53, v37, v142
	v_mul_f32_e32 v37, v233, v53
	v_mul_f32_e32 v53, v232, v53
	v_fma_f32 v37, v232, v139, -v37
	v_fmac_f32_e32 v53, v233, v139
	v_ashrrev_i32_e32 v139, 31, v138
	v_lshlrev_b64 v[140:141], 7, v[138:139]
	v_lshl_add_u64 v[140:141], v[132:133], 0, v[140:141]
	v_cvt_pk_bf16_f32 v139, v53, s0
	global_store_short v[140:141], v139, off offset:64
	v_mul_f32_e32 v139, v21, v142
	v_mul_f32_e32 v21, v5, v142
	v_mul_f32_e32 v5, v233, v21
	v_fma_f32 v5, v232, v139, -v5
	v_mul_f32_e32 v21, v232, v21
	v_or_b32_e32 v0, 0x2000, v138
	v_fmac_f32_e32 v21, v233, v139
	v_ashrrev_i32_e32 v1, 31, v0
	v_lshlrev_b64 v[0:1], 7, v[0:1]
	v_cvt_pk_bf16_f32 v138, v5, s0
	v_lshl_add_u64 v[0:1], v[132:133], 0, v[0:1]
	global_store_short v[0:1], v138, off
	v_cvt_pk_bf16_f32 v138, v21, s0
	global_store_short v[0:1], v138, off offset:64
	v_add_u32_e32 v138, 42, v136
	v_cvt_pk_bf16_f32 v143, v37, s0
	v_and_b32_e32 v139, 0x1ffe, v138
	global_store_short v[140:141], v143, off
	v_lshl_or_b32 v0, v139, 8, v137
	v_lshrrev_b32_e32 v138, 11, v138
	v_and_or_b32 v138, v138, s9, v134
	v_lshl_or_b32 v138, v138, 14, v139
	v_mul_f32_e32 v139, v54, v2
	v_mul_f32_e32 v54, v38, v2
	v_mul_f32_e32 v38, v235, v54
	v_mul_f32_e32 v54, v234, v54
	v_fma_f32 v38, v234, v139, -v38
	v_fmac_f32_e32 v54, v235, v139
	v_ashrrev_i32_e32 v139, 31, v138
	v_lshlrev_b64 v[140:141], 7, v[138:139]
	v_lshl_add_u64 v[140:141], v[132:133], 0, v[140:141]
	v_cvt_pk_bf16_f32 v139, v54, s0
	global_store_short v[140:141], v139, off offset:64
	v_mul_f32_e32 v139, v22, v2
	v_mul_f32_e32 v2, v6, v2
	v_mul_f32_e32 v6, v235, v2
	v_fma_f32 v6, v234, v139, -v6
	v_mul_f32_e32 v22, v234, v2
	v_or_b32_e32 v0, 0x2000, v138
	v_fmac_f32_e32 v22, v235, v139
	v_ashrrev_i32_e32 v1, 31, v0
	v_lshlrev_b64 v[0:1], 7, v[0:1]
	v_cvt_pk_bf16_f32 v2, v6, s0
	v_lshl_add_u64 v[0:1], v[132:133], 0, v[0:1]
	global_store_short v[0:1], v2, off
	v_cvt_pk_bf16_f32 v2, v22, s0
	v_cvt_pk_bf16_f32 v142, v38, s0
	global_store_short v[0:1], v2, off offset:64
	v_add_u32_e32 v2, 43, v136
	global_store_short v[140:141], v142, off
	v_mul_f32_e32 v140, v135, v3
	v_and_b32_e32 v3, 0x1fff, v2
	v_lshl_or_b32 v0, v3, 8, v137
	v_lshrrev_b32_e32 v2, 11, v2
	v_and_or_b32 v2, v2, s9, v134
	v_lshl_or_b32 v2, v2, 14, v3
	v_mul_f32_e32 v3, v55, v140
	v_mul_f32_e32 v55, v39, v140
	v_mul_f32_e32 v39, v237, v55
	v_mul_f32_e32 v55, v236, v55
	v_fma_f32 v39, v236, v3, -v39
	v_fmac_f32_e32 v55, v237, v3
	v_ashrrev_i32_e32 v3, 31, v2
	v_lshlrev_b64 v[138:139], 7, v[2:3]
	v_lshl_add_u64 v[138:139], v[132:133], 0, v[138:139]
	v_cvt_pk_bf16_f32 v3, v55, s0
	global_store_short v[138:139], v3, off offset:64
	v_mul_f32_e32 v3, v23, v140
	v_mul_f32_e32 v23, v7, v140
	v_mul_f32_e32 v7, v237, v23
	v_fma_f32 v7, v236, v3, -v7
	v_mul_f32_e32 v23, v236, v23
	v_or_b32_e32 v0, 0x2000, v2
	v_fmac_f32_e32 v23, v237, v3
	v_ashrrev_i32_e32 v1, 31, v0
	v_lshlrev_b64 v[0:1], 7, v[0:1]
	v_cvt_pk_bf16_f32 v2, v7, s0
	v_lshl_add_u64 v[0:1], v[132:133], 0, v[0:1]
	global_store_short v[0:1], v2, off
	v_cvt_pk_bf16_f32 v2, v23, s0
	global_store_short v[0:1], v2, off offset:64
	v_or_b32_e32 v0, 48, v144
	v_cvt_pk_bf16_f32 v141, v39, s0
	v_add_u32_e32 v140, s76, v0
	global_store_short v[138:139], v141, off
	v_and_b32_e32 v141, 0x1ffc, v140
	v_lshl_or_b32 v138, v141, 8, v137
	v_lshl_add_u32 v0, v0, 2, s8
	ds_read_b128 v[0:3], v0
	v_lshrrev_b32_e32 v140, 11, v140
	v_and_or_b32 v140, v140, s9, v134
	v_lshl_or_b32 v140, v140, 14, v141
	s_waitcnt lgkmcnt(0)
; DI u16 f2bf(float a) { return (u16)(pack2(a, 0.f) & 0xffffu); }
; DI int crow(int reg, int g) { return (reg & 3) + 8 * (reg >> 2) + 4 * g; }
; template <bool TR>
; DI void gemm_in_tile(const P& p, int l, int id, char* smem) {
;     ...
;         const int rl = 64 * wr + 32 * rb + crow(reg, g);
;         const int tok = m0 + rl;
;         const float rs = rs_s[rl] * qs;
;         const int pos = tok & 8191, b = tok >> 13;
;         const float2 cs = p.rope[pos * 32 + li];
; #pragma unroll
;         for (int c = 0; c < 2; ++c) {
;           const float x1 = acc[rb][2 * c][reg] * rs, x2 = acc[rb][2 * c + 1][reg] * rs;
;           const float o1 = x1 * cs.x - x2 * cs.y, o2 = x2 * cs.x + x1 * cs.y;
;           const size_t base = ((size_t)(((b * 4 + h) * 2 + c) * SEQ + pos)) * 64;
;           dst[base + li] = f2bf(o1);
;           dst[base + 32 + li] = f2bf(o2);
;           if (c == 0) kl0 = fmaxf(kl0, o1 * o1 + o2 * o2); else kl1 = fmaxf(kl1, o1 * o1 + o2 * o2);
	v_mul_f32_e32 v0, v135, v0
	v_mul_f32_e32 v141, v56, v0
	v_mul_f32_e32 v56, v40, v0
	v_mul_f32_e32 v2, v135, v2
	v_mul_f32_e32 v40, v239, v56
	v_mul_f32_e32 v56, v238, v56
	v_fma_f32 v40, v238, v141, -v40
	v_fmac_f32_e32 v56, v239, v141
	v_ashrrev_i32_e32 v141, 31, v140
	v_lshlrev_b64 v[142:143], 7, v[140:141]
	v_lshl_add_u64 v[142:143], v[132:133], 0, v[142:143]
	v_cvt_pk_bf16_f32 v141, v56, s0
	global_store_short v[142:143], v141, off offset:64
	v_mul_f32_e32 v141, v24, v0
	v_mul_f32_e32 v0, v8, v0
	v_mul_f32_e32 v8, v239, v0
	v_fma_f32 v8, v238, v141, -v8
	v_mul_f32_e32 v24, v238, v0
	v_or_b32_e32 v138, 0x2000, v140
	v_fmac_f32_e32 v24, v239, v141
	v_ashrrev_i32_e32 v139, 31, v138
	v_lshlrev_b64 v[138:139], 7, v[138:139]
	v_cvt_pk_bf16_f32 v0, v8, s0
	v_lshl_add_u64 v[138:139], v[132:133], 0, v[138:139]
	global_store_short v[138:139], v0, off
	v_cvt_pk_bf16_f32 v0, v24, s0
	global_store_short v[138:139], v0, off offset:64
	v_add_u32_e32 v138, 49, v136
	v_cvt_pk_bf16_f32 v145, v40, s0
	v_and_b32_e32 v139, 0x1ffd, v138
	global_store_short v[142:143], v145, off
	v_lshl_or_b32 v0, v139, 8, v137
	v_mul_f32_e32 v142, v135, v1
	v_lshrrev_b32_e32 v138, 11, v138
	v_and_or_b32 v138, v138, s9, v134
	v_lshl_or_b32 v138, v138, 14, v139
	v_mul_f32_e32 v139, v57, v142
	v_mul_f32_e32 v57, v41, v142
	v_mul_f32_e32 v41, v241, v57
	v_mul_f32_e32 v57, v240, v57
	v_fma_f32 v41, v240, v139, -v41
	v_fmac_f32_e32 v57, v241, v139
	v_ashrrev_i32_e32 v139, 31, v138
	v_lshlrev_b64 v[140:141], 7, v[138:139]
	v_lshl_add_u64 v[140:141], v[132:133], 0, v[140:141]
	v_cvt_pk_bf16_f32 v139, v57, s0
	global_store_short v[140:141], v139, off offset:64
	v_mul_f32_e32 v139, v25, v142
	v_mul_f32_e32 v25, v9, v142
	v_mul_f32_e32 v9, v241, v25
	v_fma_f32 v9, v240, v139, -v9
	v_mul_f32_e32 v25, v240, v25
	v_or_b32_e32 v0, 0x2000, v138
	v_fmac_f32_e32 v25, v241, v139
	v_ashrrev_i32_e32 v1, 31, v0
	v_lshlrev_b64 v[0:1], 7, v[0:1]
	v_cvt_pk_bf16_f32 v138, v9, s0
	v_lshl_add_u64 v[0:1], v[132:133], 0, v[0:1]
	global_store_short v[0:1], v138, off
	v_cvt_pk_bf16_f32 v138, v25, s0
	global_store_short v[0:1], v138, off offset:64
	v_add_u32_e32 v138, 50, v136
	v_cvt_pk_bf16_f32 v143, v41, s0
	v_and_b32_e32 v139, 0x1ffe, v138
	global_store_short v[140:141], v143, off
	v_lshl_or_b32 v0, v139, 8, v137
	v_lshrrev_b32_e32 v138, 11, v138
	v_and_or_b32 v138, v138, s9, v134
	v_lshl_or_b32 v138, v138, 14, v139
	v_mul_f32_e32 v139, v58, v2
	v_mul_f32_e32 v58, v42, v2
	v_mul_f32_e32 v42, v243, v58
	v_mul_f32_e32 v58, v242, v58
	v_fma_f32 v42, v242, v139, -v42
	v_fmac_f32_e32 v58, v243, v139
	v_ashrrev_i32_e32 v139, 31, v138
	v_lshlrev_b64 v[140:141], 7, v[138:139]
	v_lshl_add_u64 v[140:141], v[132:133], 0, v[140:141]
	v_cvt_pk_bf16_f32 v139, v58, s0
	global_store_short v[140:141], v139, off offset:64
	v_mul_f32_e32 v139, v26, v2
	v_mul_f32_e32 v2, v10, v2
	v_mul_f32_e32 v10, v243, v2
	v_fma_f32 v10, v242, v139, -v10
	v_mul_f32_e32 v26, v242, v2
	v_or_b32_e32 v0, 0x2000, v138
	v_fmac_f32_e32 v26, v243, v139
	v_ashrrev_i32_e32 v1, 31, v0
	v_lshlrev_b64 v[0:1], 7, v[0:1]
	v_cvt_pk_bf16_f32 v2, v10, s0
	v_lshl_add_u64 v[0:1], v[132:133], 0, v[0:1]
	global_store_short v[0:1], v2, off
	v_cvt_pk_bf16_f32 v2, v26, s0
	v_cvt_pk_bf16_f32 v142, v42, s0
	global_store_short v[0:1], v2, off offset:64
	v_add_u32_e32 v2, 51, v136
	global_store_short v[140:141], v142, off
	v_mul_f32_e32 v140, v135, v3
	v_and_b32_e32 v3, 0x1fff, v2
	v_lshl_or_b32 v0, v3, 8, v137
	v_lshrrev_b32_e32 v2, 11, v2
	v_and_or_b32 v2, v2, s9, v134
	v_lshl_or_b32 v2, v2, 14, v3
	v_mul_f32_e32 v3, v59, v140
	v_mul_f32_e32 v59, v43, v140
	v_mul_f32_e32 v43, v245, v59
	v_mul_f32_e32 v59, v244, v59
	v_fma_f32 v43, v244, v3, -v43
	v_fmac_f32_e32 v59, v245, v3
	v_ashrrev_i32_e32 v3, 31, v2
	v_lshlrev_b64 v[138:139], 7, v[2:3]
	v_lshl_add_u64 v[138:139], v[132:133], 0, v[138:139]
	v_cvt_pk_bf16_f32 v3, v59, s0
	global_store_short v[138:139], v3, off offset:64
	v_mul_f32_e32 v3, v27, v140
	v_mul_f32_e32 v27, v11, v140
	v_mul_f32_e32 v11, v245, v27
	v_fma_f32 v11, v244, v3, -v11
	v_mul_f32_e32 v27, v244, v27
	v_or_b32_e32 v0, 0x2000, v2
	v_fmac_f32_e32 v27, v245, v3
	v_ashrrev_i32_e32 v1, 31, v0
	v_lshlrev_b64 v[0:1], 7, v[0:1]
	v_cvt_pk_bf16_f32 v2, v11, s0
	v_lshl_add_u64 v[0:1], v[132:133], 0, v[0:1]
	global_store_short v[0:1], v2, off
	v_cvt_pk_bf16_f32 v2, v27, s0
	global_store_short v[0:1], v2, off offset:64
	v_or_b32_e32 v0, 56, v144
	v_add_u32_e32 v140, s76, v0
	v_lshl_add_u32 v0, v0, 2, s8
	ds_read_b128 v[0:3], v0
	v_cvt_pk_bf16_f32 v141, v43, s0
	global_store_short v[138:139], v141, off
	s_waitcnt lgkmcnt(0)
; DI u16 f2bf(float a) { return (u16)(pack2(a, 0.f) & 0xffffu); }
; DI int crow(int reg, int g) { return (reg & 3) + 8 * (reg >> 2) + 4 * g; }
; template <bool TR>
; DI void gemm_in_tile(const P& p, int l, int id, char* smem) {
;     ...
;         const int rl = 64 * wr + 32 * rb + crow(reg, g);
;         const int tok = m0 + rl;
;         const float rs = rs_s[rl] * qs;
;         const int pos = tok & 8191, b = tok >> 13;
;         const float2 cs = p.rope[pos * 32 + li];
; #pragma unroll
;         for (int c = 0; c < 2; ++c) {
;           const float x1 = acc[rb][2 * c][reg] * rs, x2 = acc[rb][2 * c + 1][reg] * rs;
;           const float o1 = x1 * cs.x - x2 * cs.y, o2 = x2 * cs.x + x1 * cs.y;
;           const size_t base = ((size_t)(((b * 4 + h) * 2 + c) * SEQ + pos)) * 64;
;           dst[base + li] = f2bf(o1);
;           dst[base + 32 + li] = f2bf(o2);
;           if (c == 0) kl0 = fmaxf(kl0, o1 * o1 + o2 * o2); else kl1 = fmaxf(kl1, o1 * o1 + o2 * o2);
	v_mul_f32_e32 v144, v135, v0
	v_and_b32_e32 v0, 0x1ffc, v140
	v_lshl_or_b32 v138, v0, 8, v137
	v_lshrrev_b32_e32 v140, 11, v140
	v_and_or_b32 v140, v140, s9, v134
	v_lshl_or_b32 v140, v140, 14, v0
	v_mul_f32_e32 v44, v44, v144
	v_mul_f32_e32 v60, v60, v144
	v_ashrrev_i32_e32 v141, 31, v140
	v_lshlrev_b64 v[142:143], 7, v[140:141]
	v_lshl_add_u64 v[142:143], v[132:133], 0, v[142:143]
	v_mul_f32_e32 v0, v247, v44
	v_fma_f32 v0, v246, v60, -v0
	v_mul_f32_e32 v44, v246, v44
	v_fmac_f32_e32 v44, v247, v60
	v_cvt_pk_bf16_f32 v60, v0, s0
	global_store_short v[142:143], v60, off
	v_cvt_pk_bf16_f32 v60, v44, s0
	global_store_short v[142:143], v60, off offset:64
	v_mul_f32_e32 v60, v28, v144
	v_mul_f32_e32 v28, v12, v144
	v_mul_f32_e32 v12, v247, v28
	v_fma_f32 v12, v246, v60, -v12
	v_mul_f32_e32 v28, v246, v28
	v_or_b32_e32 v138, 0x2000, v140
	v_fmac_f32_e32 v28, v247, v60
	v_ashrrev_i32_e32 v139, 31, v138
	v_lshlrev_b64 v[138:139], 7, v[138:139]
	v_cvt_pk_bf16_f32 v60, v12, s0
	v_lshl_add_u64 v[138:139], v[132:133], 0, v[138:139]
	global_store_short v[138:139], v60, off
	v_cvt_pk_bf16_f32 v60, v28, s0
	global_store_short v[138:139], v60, off offset:64
	v_add_u32_e32 v60, 57, v136
	v_mul_f32_e32 v142, v135, v1
	v_and_b32_e32 v1, 0x1ffd, v60
	v_lshl_or_b32 v138, v1, 8, v137
	v_lshrrev_b32_e32 v60, 11, v60
	v_and_or_b32 v60, v60, s9, v134
	v_mul_f32_e32 v45, v45, v142
	v_lshl_or_b32 v60, v60, 14, v1
	v_mul_f32_e32 v61, v61, v142
	v_mul_f32_e32 v1, v191, v45
	v_mul_f32_e32 v45, v190, v45
	v_fma_f32 v1, v190, v61, -v1
	v_fmac_f32_e32 v45, v191, v61
	v_ashrrev_i32_e32 v61, 31, v60
	v_lshlrev_b64 v[140:141], 7, v[60:61]
	v_lshl_add_u64 v[140:141], v[132:133], 0, v[140:141]
	v_cvt_pk_bf16_f32 v61, v45, s0
	global_store_short v[140:141], v61, off offset:64
	v_mul_f32_e32 v61, v29, v142
	v_mul_f32_e32 v29, v13, v142
	v_mul_f32_e32 v13, v191, v29
	v_mul_f32_e32 v29, v190, v29
	v_or_b32_e32 v60, 0x2000, v60
	v_fma_f32 v13, v190, v61, -v13
	v_fmac_f32_e32 v29, v191, v61
	v_ashrrev_i32_e32 v61, 31, v60
	v_lshlrev_b64 v[60:61], 7, v[60:61]
	v_cvt_pk_bf16_f32 v138, v13, s0
	v_lshl_add_u64 v[60:61], v[132:133], 0, v[60:61]
	global_store_short v[60:61], v138, off
	v_cvt_pk_bf16_f32 v138, v29, s0
	global_store_short v[60:61], v138, off offset:64
	v_add_u32_e32 v138, 58, v136
	v_cvt_pk_bf16_f32 v143, v1, s0
	v_mul_f32_e32 v142, v135, v2
	v_and_b32_e32 v2, 0x1ffe, v138
	global_store_short v[140:141], v143, off
	v_lshl_or_b32 v60, v2, 8, v137
	v_lshrrev_b32_e32 v138, 11, v138
	v_and_or_b32 v138, v138, s9, v134
	v_lshl_or_b32 v138, v138, 14, v2
	v_mul_f32_e32 v46, v46, v142
	v_mul_f32_e32 v62, v62, v142
	v_ashrrev_i32_e32 v139, 31, v138
	v_lshlrev_b64 v[140:141], 7, v[138:139]
	v_lshl_add_u64 v[140:141], v[132:133], 0, v[140:141]
	v_mul_f32_e32 v135, v135, v3
	v_mul_f32_e32 v47, v47, v135
	v_mul_f32_e32 v63, v63, v135
	v_mul_f32_e32 v2, v193, v46
	v_fma_f32 v2, v192, v62, -v2
	v_mul_f32_e32 v46, v192, v46
	v_fmac_f32_e32 v46, v193, v62
	v_cvt_pk_bf16_f32 v62, v2, s0
	global_store_short v[140:141], v62, off
	v_cvt_pk_bf16_f32 v62, v46, s0
	global_store_short v[140:141], v62, off offset:64
	v_mul_f32_e32 v62, v30, v142
	v_mul_f32_e32 v30, v14, v142
	v_mul_f32_e32 v14, v193, v30
	v_fma_f32 v14, v192, v62, -v14
	v_mul_f32_e32 v30, v192, v30
	v_or_b32_e32 v60, 0x2000, v138
	v_fmac_f32_e32 v30, v193, v62
	v_ashrrev_i32_e32 v61, 31, v60
	v_lshlrev_b64 v[60:61], 7, v[60:61]
	v_cvt_pk_bf16_f32 v62, v14, s0
	v_lshl_add_u64 v[60:61], v[132:133], 0, v[60:61]
	global_store_short v[60:61], v62, off
	v_cvt_pk_bf16_f32 v62, v30, s0
	global_store_short v[60:61], v62, off offset:64
	v_add_u32_e32 v62, 59, v136
	v_and_b32_e32 v3, 0x1fff, v62
	v_lshl_or_b32 v60, v3, 8, v137
	v_lshrrev_b32_e32 v62, 11, v62
	v_and_or_b32 v62, v62, s9, v134
	v_lshl_or_b32 v62, v62, 14, v3
	v_mul_f32_e32 v3, v195, v47
	v_mul_f32_e32 v47, v194, v47
	v_fma_f32 v3, v194, v63, -v3
	v_fmac_f32_e32 v47, v195, v63
	v_ashrrev_i32_e32 v63, 31, v62
	v_lshlrev_b64 v[136:137], 7, v[62:63]
	v_lshl_add_u64 v[136:137], v[132:133], 0, v[136:137]
	v_cvt_pk_bf16_f32 v63, v47, s0
	global_store_short v[136:137], v63, off offset:64
	v_mul_f32_e32 v63, v31, v135
	v_mul_f32_e32 v31, v15, v135
	v_mul_f32_e32 v15, v195, v31
	v_fma_f32 v15, v194, v63, -v15
	v_mul_f32_e32 v31, v194, v31
	v_or_b32_e32 v60, 0x2000, v62
	v_fmac_f32_e32 v31, v195, v63
	v_ashrrev_i32_e32 v61, 31, v60
	v_lshlrev_b64 v[60:61], 7, v[60:61]
	v_cvt_pk_bf16_f32 v62, v15, s0
	v_lshl_add_u64 v[60:61], v[132:133], 0, v[60:61]
	v_cvt_pk_bf16_f32 v138, v3, s0
	global_store_short v[60:61], v62, off
	v_cvt_pk_bf16_f32 v62, v31, s0
	global_store_short v[136:137], v138, off
	global_store_short v[60:61], v62, off offset:64
	s_cbranch_vccnz .LBB0_337
; template <bool TR>
; DI void gemm_in_tile(const P& p, int l, int id, char* smem) {
;     ...
;           if (c == 0) kl0 = fmaxf(kl0, o1 * o1 + o2 * o2); else kl1 = fmaxf(kl1, o1 * o1 + o2 * o2);
;         }
;       }
;     }
;     if (!isq) {
; #pragma unroll
;       for (int m = 16; m >= 1; m >>= 1) { kl0 += __shfl_xor(kl0, m); kl1 += __shfl_xor(kl1, m); }
;       kl0 = fmaxf(kl0, __shfl_xor(kl0, 32)) * 1.02f;
;       kl1 = fmaxf(kl1, __shfl_xor(kl1, 32)) * 1.02f;
;       if (lane == 0) {
;         atomicMax(p.kmax + (m0 >> 13) * 8 + h * 2 + 0, __float_as_uint(kl0));
;         atomicMax(p.kmax + (m0 >> 13) * 8 + h * 2 + 1, __float_as_uint(kl1));
;       }
	v_mul_f32_e32 v60, v128, v128
	v_mul_f32_e32 v61, v129, v129
	v_fmac_f32_e32 v60, v80, v80
	v_fmac_f32_e32 v61, v81, v81
	v_max3_f32 v60, v60, 0, v61
	v_mul_f32_e32 v61, v130, v130
	v_mul_f32_e32 v62, v131, v131
	v_fmac_f32_e32 v61, v82, v82
	v_fmac_f32_e32 v62, v83, v83
	v_max3_f32 v60, v60, v61, v62
	v_mul_f32_e32 v61, v84, v84
	v_mul_f32_e32 v62, v85, v85
	v_fmac_f32_e32 v61, v68, v68
	v_fmac_f32_e32 v62, v69, v69
	v_max3_f32 v60, v60, v61, v62
	v_mul_f32_e32 v61, v86, v86
	v_mul_f32_e32 v62, v87, v87
	v_fmac_f32_e32 v61, v70, v70
	v_fmac_f32_e32 v62, v71, v71
	v_max3_f32 v60, v60, v61, v62
	v_mul_f32_e32 v61, v88, v88
	v_mul_f32_e32 v62, v89, v89
	v_fmac_f32_e32 v61, v72, v72
	v_fmac_f32_e32 v62, v73, v73
	v_max3_f32 v60, v60, v61, v62
	v_mul_f32_e32 v61, v90, v90
	v_mul_f32_e32 v62, v91, v91
	v_fmac_f32_e32 v61, v74, v74
	v_fmac_f32_e32 v62, v75, v75
	v_max3_f32 v60, v60, v61, v62
	v_mul_f32_e32 v61, v92, v92
	v_mul_f32_e32 v62, v93, v93
	v_fmac_f32_e32 v61, v76, v76
	v_fmac_f32_e32 v62, v77, v77
	v_max3_f32 v60, v60, v61, v62
	v_mul_f32_e32 v61, v94, v94
	v_mul_f32_e32 v62, v95, v95
	v_fmac_f32_e32 v61, v78, v78
	v_fmac_f32_e32 v62, v79, v79
	v_max3_f32 v60, v60, v61, v62
	v_mul_f32_e32 v61, v64, v64
	v_fmac_f32_e32 v61, v16, v16
	v_mul_f32_e32 v16, v65, v65
	v_fmac_f32_e32 v16, v17, v17
	v_mul_f32_e32 v17, v66, v66
	v_fmac_f32_e32 v17, v18, v18
	v_mul_f32_e32 v18, v67, v67
	v_max3_f32 v16, v60, v61, v16
	v_fmac_f32_e32 v18, v19, v19
	v_max3_f32 v16, v16, v17, v18
	v_mul_f32_e32 v17, v20, v20
	v_fmac_f32_e32 v17, v4, v4
	v_mul_f32_e32 v4, v21, v21
	v_fmac_f32_e32 v4, v5, v5
	v_mul_f32_e32 v5, v22, v22
	v_fmac_f32_e32 v5, v6, v6
	v_mul_f32_e32 v6, v23, v23
	v_max3_f32 v4, v16, v17, v4
	v_fmac_f32_e32 v6, v7, v7
	v_max3_f32 v4, v4, v5, v6
	v_mul_f32_e32 v5, v24, v24
	v_mul_f32_e32 v6, v25, v25
	v_fmac_f32_e32 v5, v8, v8
	v_fmac_f32_e32 v6, v9, v9
	v_max3_f32 v4, v4, v5, v6
	v_mul_f32_e32 v5, v26, v26
	v_mul_f32_e32 v6, v27, v27
	v_fmac_f32_e32 v5, v10, v10
	v_fmac_f32_e32 v6, v11, v11
	v_max3_f32 v4, v4, v5, v6
	v_mul_f32_e32 v5, v28, v28
	v_mul_f32_e32 v6, v29, v29
	v_fmac_f32_e32 v5, v12, v12
	v_fmac_f32_e32 v6, v13, v13
	v_max3_f32 v4, v4, v5, v6
	v_mul_f32_e32 v5, v30, v30
	v_mul_f32_e32 v6, v31, v31
	v_fmac_f32_e32 v5, v14, v14
	v_fmac_f32_e32 v6, v15, v15
	v_max3_f32 v4, v4, v5, v6
	v_mul_f32_e32 v5, v112, v112
	v_mul_f32_e32 v6, v113, v113
	v_fmac_f32_e32 v5, v96, v96
	v_fmac_f32_e32 v6, v97, v97
	v_max3_f32 v5, v5, 0, v6
	v_mul_f32_e32 v6, v114, v114
	v_mul_f32_e32 v7, v115, v115
	v_fmac_f32_e32 v6, v98, v98
	v_fmac_f32_e32 v7, v99, v99
	v_max3_f32 v5, v5, v6, v7
	v_mul_f32_e32 v6, v116, v116
	v_mul_f32_e32 v7, v117, v117
	v_fmac_f32_e32 v6, v100, v100
	v_fmac_f32_e32 v7, v101, v101
	v_max3_f32 v5, v5, v6, v7
	v_mul_f32_e32 v6, v118, v118
	v_mul_f32_e32 v7, v119, v119
	v_fmac_f32_e32 v6, v102, v102
	v_fmac_f32_e32 v7, v103, v103
	v_max3_f32 v5, v5, v6, v7
	v_mul_f32_e32 v6, v120, v120
	v_mul_f32_e32 v7, v121, v121
	v_fmac_f32_e32 v6, v104, v104
	v_fmac_f32_e32 v7, v105, v105
	v_max3_f32 v5, v5, v6, v7
	v_mul_f32_e32 v6, v122, v122
	v_mul_f32_e32 v7, v123, v123
	v_fmac_f32_e32 v6, v106, v106
	v_fmac_f32_e32 v7, v107, v107
	v_max3_f32 v5, v5, v6, v7
	v_mul_f32_e32 v6, v124, v124
	v_mul_f32_e32 v7, v125, v125
	v_fmac_f32_e32 v6, v108, v108
	v_fmac_f32_e32 v7, v109, v109
	v_max3_f32 v5, v5, v6, v7
	v_mul_f32_e32 v6, v126, v126
	v_mul_f32_e32 v7, v127, v127
	v_fmac_f32_e32 v6, v110, v110
	v_fmac_f32_e32 v7, v111, v111
	v_max3_f32 v5, v5, v6, v7
	v_mul_f32_e32 v6, v48, v48
	v_mul_f32_e32 v7, v49, v49
	v_fmac_f32_e32 v6, v32, v32
	v_fmac_f32_e32 v7, v33, v33
	v_max3_f32 v5, v5, v6, v7
	v_mul_f32_e32 v6, v50, v50
	v_mul_f32_e32 v7, v51, v51
	v_fmac_f32_e32 v6, v34, v34
	v_fmac_f32_e32 v7, v35, v35
	v_max3_f32 v5, v5, v6, v7
	v_mul_f32_e32 v6, v52, v52
	v_mul_f32_e32 v7, v53, v53
	v_fmac_f32_e32 v6, v36, v36
	v_fmac_f32_e32 v7, v37, v37
	v_max3_f32 v5, v5, v6, v7
	v_mul_f32_e32 v6, v54, v54
	v_mul_f32_e32 v7, v55, v55
	v_fmac_f32_e32 v6, v38, v38
	v_fmac_f32_e32 v7, v39, v39
	v_max3_f32 v5, v5, v6, v7
	v_mul_f32_e32 v6, v56, v56
	v_mul_f32_e32 v7, v57, v57
	v_fmac_f32_e32 v6, v40, v40
	v_fmac_f32_e32 v7, v41, v41
	v_max3_f32 v5, v5, v6, v7
	v_mul_f32_e32 v6, v58, v58
	v_mul_f32_e32 v7, v59, v59
	v_fmac_f32_e32 v6, v42, v42
	v_fmac_f32_e32 v7, v43, v43
	v_max3_f32 v5, v5, v6, v7
	v_mul_f32_e32 v6, v44, v44
	v_fmac_f32_e32 v6, v0, v0
	v_mul_f32_e32 v0, v45, v45
	v_fmac_f32_e32 v0, v1, v1
	v_mul_f32_e32 v1, v46, v46
	v_fmac_f32_e32 v1, v2, v2
	v_mul_f32_e32 v2, v47, v47
	v_max3_f32 v0, v5, v6, v0
	v_fmac_f32_e32 v2, v3, v3
	v_max3_f32 v0, v0, v1, v2
	v_and_b32_e32 v1, 64, v215
	v_add_u32_e32 v2, 64, v1
	v_xor_b32_e32 v1, 16, v215
	v_cmp_lt_i32_e32 vcc, v1, v2
	s_nop 1
	v_cndmask_b32_e32 v1, v215, v1, vcc
	v_lshlrev_b32_e32 v1, 2, v1
	ds_bpermute_b32 v3, v1, v0
	ds_bpermute_b32 v1, v1, v4
	s_waitcnt lgkmcnt(1)
	v_add_f32_e32 v0, v0, v3
	v_xor_b32_e32 v3, 8, v215
	v_cmp_lt_i32_e32 vcc, v3, v2
	s_waitcnt lgkmcnt(0)
	v_add_f32_e32 v1, v4, v1
	v_cndmask_b32_e32 v3, v215, v3, vcc
	v_lshlrev_b32_e32 v3, 2, v3
	ds_bpermute_b32 v4, v3, v0
	ds_bpermute_b32 v3, v3, v1
	s_waitcnt lgkmcnt(1)
	v_add_f32_e32 v0, v0, v4
	s_waitcnt lgkmcnt(0)
	v_add_f32_e32 v1, v1, v3
	v_xor_b32_e32 v3, 4, v215
	v_cmp_lt_i32_e32 vcc, v3, v2
	s_nop 1
	v_cndmask_b32_e32 v3, v215, v3, vcc
	v_lshlrev_b32_e32 v3, 2, v3
	ds_bpermute_b32 v4, v3, v0
	ds_bpermute_b32 v3, v3, v1
	s_waitcnt lgkmcnt(1)
	v_add_f32_e32 v0, v0, v4
	s_waitcnt lgkmcnt(0)
	v_add_f32_e32 v1, v1, v3
	v_xor_b32_e32 v3, 2, v215
	v_cmp_lt_i32_e32 vcc, v3, v2
	s_nop 1
	v_cndmask_b32_e32 v3, v215, v3, vcc
	v_lshlrev_b32_e32 v3, 2, v3
	ds_bpermute_b32 v4, v3, v0
	ds_bpermute_b32 v3, v3, v1
	s_waitcnt lgkmcnt(1)
	v_add_f32_e32 v0, v0, v4
	s_waitcnt lgkmcnt(0)
	v_add_f32_e32 v1, v1, v3
	v_xor_b32_e32 v3, 1, v215
	v_cmp_lt_i32_e32 vcc, v3, v2
	s_nop 1
	v_cndmask_b32_e32 v3, v215, v3, vcc
	v_lshlrev_b32_e32 v3, 2, v3
	ds_bpermute_b32 v4, v3, v0
	ds_bpermute_b32 v3, v3, v1
	s_waitcnt lgkmcnt(1)
	v_add_f32_e32 v0, v0, v4
	s_waitcnt lgkmcnt(0)
	v_add_f32_e32 v1, v1, v3
	v_xor_b32_e32 v3, 32, v215
	v_cmp_lt_i32_e32 vcc, v3, v2
	v_and_b32_e32 v4, 63, v176
	s_nop 0
	v_cndmask_b32_e32 v2, v215, v3, vcc
	v_lshlrev_b32_e32 v3, 2, v2
	ds_bpermute_b32 v2, v3, v0
	ds_bpermute_b32 v3, v3, v1
	v_cmp_eq_u32_e32 vcc, 0, v4
	s_and_saveexec_b64 s[8:9], vcc
	s_cbranch_execz .LBB0_336
	s_waitcnt lgkmcnt(1)
	v_max_f32_e32 v2, v2, v2
	v_max_f32_e32 v0, v0, v0
	s_and_b32 s56, s75, 32
	v_readlane_b32 s76, v248, 26
	s_waitcnt lgkmcnt(0)
	v_max_f32_e32 v3, v3, v3
	v_max_f32_e32 v1, v1, v1
	v_max_f32_e32 v0, v0, v2
	v_readlane_b32 s77, v248, 27
	s_add_u32 s76, s76, s56
	v_max_f32_e32 v1, v1, v3
	v_mul_f32_e32 v0, 0x3f828f5c, v0
	s_addc_u32 s77, s77, 0
	v_lshlrev_b32_e32 v2, 3, v134
	v_mul_f32_e32 v1, 0x3f828f5c, v1
	global_atomic_umax v2, v0, s[76:77]
	global_atomic_umax v2, v1, s[76:77] offset:4
